# prologue phase: layer-0 gate/up/in weight conversion through the pair-merged pipelined routine (full-line row loads), units assigned in reverse wave order
# speedup vs baseline: 1.0049x; 1.0049x over previous
.LBB0_817:
	v_readlane_b32 s0, v253, 45
	v_readlane_b32 s1, v253, 46
	s_mulk_i32 s0, 0x4200
	s_add_i32 s4, s97, s0
	v_readlane_b32 s0, v253, 41
	v_readlane_b32 s1, v253, 42
	s_add_u32 s5, s0, 0x1000000
	s_addc_u32 s6, s1, 0
	v_and_b32_e32 v0, 3, v237
	v_and_b32_e32 v19, 16, v237
	v_lshrrev_b32_e32 v3, 5, v238
	v_lshrrev_b32_e32 v14, 3, v238
	v_lshlrev_b32_e32 v4, 3, v238
	s_cmpk_gt_i32 s10, 0x1a7f
	v_lshrrev_b32_e32 v22, 2, v237
	v_and_b32_e32 v8, 31, v237
	v_and_or_b32 v15, v2, 24, v0
	v_cmp_eq_u32_e32 vcc, 0, v19
	v_mul_u32_u24_e32 v21, 0x84, v3
	v_and_b32_e32 v2, 56, v4
	v_lshlrev_b32_e32 v20, 2, v14
	v_or_b32_e32 v16, 8, v14
	v_or_b32_e32 v17, 16, v14
	v_or_b32_e32 v18, 24, v14
	s_cbranch_scc1 .LBB0_824
	v_readlane_b32 s0, v253, 43
	v_readlane_b32 s1, v253, 45
	s_lshl_b32 s4, s0, 3
	s_add_i32 s4, s4, s1
	s_sub_i32 s4, 0x7ff, s4
	s_movk_i32 s24, 0x800
	s_movk_i32 s25, 0xf80
	v_readlane_b32 s0, v253, 45
	s_mulk_i32 s0, 0x4200
	s_add_i32 s0, s97, s0
	v_readlane_b32 s22, v253, 41
	v_readlane_b32 s23, v253, 42
	v_readlane_b32 s6, v252, 1
	v_readlane_b32 s7, v252, 2
	s_load_dwordx4 s[8:11], s[6:7], 0x48
	s_load_dwordx2 s[14:15], s[6:7], 0x60
	v_lshlrev_b32_e32 v0, 1, v238
	v_and_b32_e32 v8, 3, v237
	v_and_or_b32 v8, v0, 24, v8
	v_lshrrev_b32_e32 v9, 2, v237
	v_and_or_b32 v9, v9, 4, v8
	v_lshlrev_b32_e32 v9, 2, v9
	v_lshrrev_b32_e32 v7, 5, v238
	v_lshrrev_b32_e32 v12, 3, v238
	v_lshlrev_b32_e32 v11, 3, v238
	v_and_b32_e32 v11, 56, v11
	v_lshlrev_b32_e32 v10, 1, v11
	v_lshl_add_u32 v4, v12, 11, v10
	v_and_b32_e32 v10, 31, v237
	v_lshlrev_b32_e32 v8, 2, v10
	v_mul_u32_u24_e32 v2, 0x84, v7
	v_add3_u32 v13, s0, v8, v2
	v_add_u32_e32 v14, 0x400, v13
	v_add_u32_e32 v15, 0x800, v13
	v_add_u32_e32 v16, 0xc00, v13
	v_add_u32_e32 v17, 0x1000, v13
	v_add_u32_e32 v18, 0x1400, v13
	v_add_u32_e32 v19, 0x1800, v13
	v_add_u32_e32 v20, 0x1c00, v13
	v_bfe_u32 v3, v10, 2, 1
	v_mul_u32_u24_e32 v3, 0x2100, v3
	v_lshrrev_b32_e32 v0, 3, v10
	v_lshlrev_b32_e32 v0, 2, v0
	v_and_b32_e32 v10, 3, v10
	v_or_b32_e32 v0, v0, v10
	v_lshlrev_b32_e32 v0, 2, v0
	v_add3_u32 v0, v0, v2, v3
	v_add_u32_e32 v144, s0, v0
	v_add_u32_e32 v145, 0x400, v144
	v_add_u32_e32 v146, 0x800, v144
	v_add_u32_e32 v147, 0xc00, v144
	v_add_u32_e32 v148, 0x1000, v144
	v_add_u32_e32 v149, 0x1400, v144
	v_add_u32_e32 v150, 0x1800, v144
	v_add_u32_e32 v151, 0x1c00, v144
	v_add_u32_e32 v152, 64, v144
	v_add_u32_e32 v153, 64, v145
	v_add_u32_e32 v154, 64, v146
	v_add_u32_e32 v155, 64, v147
	v_add_u32_e32 v156, 64, v148
	v_add_u32_e32 v157, 64, v149
	v_add_u32_e32 v158, 64, v150
	v_add_u32_e32 v159, 64, v151
	v_mul_u32_u24_e32 v10, 0x84, v11
	v_lshlrev_b32_e32 v2, 2, v12
	v_add3_u32 v21, s0, v10, v2
	v_mov_b32_e32 v11, v1
	s_waitcnt lgkmcnt(0)
	v_mul_u32_u24_e32 v10, 0x2c00, v7
	v_add_u32_e32 v10, v10, v8
	v_lshl_add_u64 v[136:137], s[8:9], 0, v[10:11]
	v_lshl_add_u64 v[138:139], s[10:11], 0, v[10:11]
	v_mul_u32_u24_e32 v10, 0x2400, v7
	v_add_u32_e32 v10, v10, v9
	v_lshl_add_u64 v[140:141], s[14:15], 0, v[10:11]
	s_cmpk_lt_u32 s4, 0xb00
	s_cbranch_scc0 .Lcvp_in1
	s_cmpk_gt_u32 s4, 0x57f
	s_cselect_b32 s5, 1, 0
	s_mul_i32 s6, s5, 0x580
	s_sub_i32 s6, s4, s6
	s_mul_i32 s7, s6, 0x2e9
	s_lshr_b32 s7, s7, 16
	s_mul_i32 s8, s7, 0x58
	s_sub_i32 s6, s6, s8
	s_lshr_b32 s8, s6, 2
	s_and_b32 s9, s6, 3
	s_lshl_b32 s10, s8, 9
	s_lshl_b32 s11, s9, 7
	s_add_i32 s10, s10, s11
	s_mul_i32 s11, s5, 0xb00000
	s_add_u32 s10, s10, s11
	s_mul_i32 s11, s7, 0xb0000
	s_add_u32 s10, s10, s11
	s_mov_b32 s11, 0
	v_lshl_add_u64 v[22:23], v[136:137], 0, s[10:11]
	v_lshl_add_u64 v[142:143], v[138:139], 0, s[10:11]
	s_mov_b64 s[26:27], 0x5800
	s_lshl_b32 s8, s8, 3
	s_add_i32 s8, s8, s9
	s_mul_i32 s9, s5, 0xf80000
	s_lshl_b32 s8, s8, 16
	s_add_u32 s8, s8, s9
	s_lshl_b32 s9, s7, 7
	s_add_u32 s8, s8, s9
	s_add_u32 s8, s8, 0x1000000
	s_add_u32 s12, s22, s8
	s_addc_u32 s13, s23, 0
	s_mov_b32 s1, 1
	global_load_dword v24, v[22:23], off nt
	v_lshl_add_u64 v[22:23], v[22:23], 0, s[26:27]
	global_load_dword v25, v[22:23], off nt
	v_lshl_add_u64 v[22:23], v[22:23], 0, s[26:27]
	global_load_dword v26, v[22:23], off nt
	v_lshl_add_u64 v[22:23], v[22:23], 0, s[26:27]
	global_load_dword v27, v[22:23], off nt
	v_lshl_add_u64 v[22:23], v[22:23], 0, s[26:27]
	global_load_dword v28, v[22:23], off nt
	v_lshl_add_u64 v[22:23], v[22:23], 0, s[26:27]
	global_load_dword v29, v[22:23], off nt
	v_lshl_add_u64 v[22:23], v[22:23], 0, s[26:27]
	global_load_dword v30, v[22:23], off nt
	v_lshl_add_u64 v[22:23], v[22:23], 0, s[26:27]
	global_load_dword v31, v[22:23], off nt
	v_lshl_add_u64 v[22:23], v[22:23], 0, s[26:27]
	global_load_dword v32, v[22:23], off nt
	v_lshl_add_u64 v[22:23], v[22:23], 0, s[26:27]
	global_load_dword v33, v[22:23], off nt
	v_lshl_add_u64 v[22:23], v[22:23], 0, s[26:27]
	global_load_dword v34, v[22:23], off nt
	v_lshl_add_u64 v[22:23], v[22:23], 0, s[26:27]
	global_load_dword v35, v[22:23], off nt
	v_lshl_add_u64 v[22:23], v[22:23], 0, s[26:27]
	global_load_dword v36, v[22:23], off nt
	v_lshl_add_u64 v[22:23], v[22:23], 0, s[26:27]
	global_load_dword v37, v[22:23], off nt
	v_lshl_add_u64 v[22:23], v[22:23], 0, s[26:27]
	global_load_dword v38, v[22:23], off nt
	v_lshl_add_u64 v[22:23], v[22:23], 0, s[26:27]
	global_load_dword v39, v[22:23], off nt
	v_lshl_add_u64 v[22:23], v[22:23], 0, s[26:27]
	global_load_dword v40, v[22:23], off nt
	v_lshl_add_u64 v[22:23], v[22:23], 0, s[26:27]
	global_load_dword v41, v[22:23], off nt
	v_lshl_add_u64 v[22:23], v[22:23], 0, s[26:27]
	global_load_dword v42, v[22:23], off nt
	v_lshl_add_u64 v[22:23], v[22:23], 0, s[26:27]
	global_load_dword v43, v[22:23], off nt
	v_lshl_add_u64 v[22:23], v[22:23], 0, s[26:27]
	global_load_dword v44, v[22:23], off nt
	v_lshl_add_u64 v[22:23], v[22:23], 0, s[26:27]
	global_load_dword v45, v[22:23], off nt
	v_lshl_add_u64 v[22:23], v[22:23], 0, s[26:27]
	global_load_dword v46, v[22:23], off nt
	v_lshl_add_u64 v[22:23], v[22:23], 0, s[26:27]
	global_load_dword v47, v[22:23], off nt
	v_lshl_add_u64 v[22:23], v[22:23], 0, s[26:27]
	global_load_dword v48, v[22:23], off nt
	v_lshl_add_u64 v[22:23], v[22:23], 0, s[26:27]
	global_load_dword v49, v[22:23], off nt
	v_lshl_add_u64 v[22:23], v[22:23], 0, s[26:27]
	global_load_dword v50, v[22:23], off nt
	v_lshl_add_u64 v[22:23], v[22:23], 0, s[26:27]
	global_load_dword v51, v[22:23], off nt
	v_lshl_add_u64 v[22:23], v[22:23], 0, s[26:27]
	global_load_dword v52, v[22:23], off nt
	v_lshl_add_u64 v[22:23], v[22:23], 0, s[26:27]
	global_load_dword v53, v[22:23], off nt
	v_lshl_add_u64 v[22:23], v[22:23], 0, s[26:27]
	global_load_dword v54, v[22:23], off nt
	v_lshl_add_u64 v[22:23], v[22:23], 0, s[26:27]
	global_load_dword v55, v[22:23], off nt
	global_load_dword v56, v[142:143], off nt
	v_lshl_add_u64 v[142:143], v[142:143], 0, s[26:27]
	global_load_dword v57, v[142:143], off nt
	v_lshl_add_u64 v[142:143], v[142:143], 0, s[26:27]
	global_load_dword v58, v[142:143], off nt
	v_lshl_add_u64 v[142:143], v[142:143], 0, s[26:27]
	global_load_dword v59, v[142:143], off nt
	v_lshl_add_u64 v[142:143], v[142:143], 0, s[26:27]
	global_load_dword v60, v[142:143], off nt
	v_lshl_add_u64 v[142:143], v[142:143], 0, s[26:27]
	global_load_dword v61, v[142:143], off nt
	v_lshl_add_u64 v[142:143], v[142:143], 0, s[26:27]
	global_load_dword v62, v[142:143], off nt
	v_lshl_add_u64 v[142:143], v[142:143], 0, s[26:27]
	global_load_dword v63, v[142:143], off nt
	v_lshl_add_u64 v[142:143], v[142:143], 0, s[26:27]
	global_load_dword v64, v[142:143], off nt
	v_lshl_add_u64 v[142:143], v[142:143], 0, s[26:27]
	global_load_dword v65, v[142:143], off nt
	v_lshl_add_u64 v[142:143], v[142:143], 0, s[26:27]
	global_load_dword v66, v[142:143], off nt
	v_lshl_add_u64 v[142:143], v[142:143], 0, s[26:27]
	global_load_dword v67, v[142:143], off nt
	v_lshl_add_u64 v[142:143], v[142:143], 0, s[26:27]
	global_load_dword v68, v[142:143], off nt
	v_lshl_add_u64 v[142:143], v[142:143], 0, s[26:27]
	global_load_dword v69, v[142:143], off nt
	v_lshl_add_u64 v[142:143], v[142:143], 0, s[26:27]
	global_load_dword v70, v[142:143], off nt
	v_lshl_add_u64 v[142:143], v[142:143], 0, s[26:27]
	global_load_dword v71, v[142:143], off nt
	v_lshl_add_u64 v[142:143], v[142:143], 0, s[26:27]
	global_load_dword v72, v[142:143], off nt
	v_lshl_add_u64 v[142:143], v[142:143], 0, s[26:27]
	global_load_dword v73, v[142:143], off nt
	v_lshl_add_u64 v[142:143], v[142:143], 0, s[26:27]
	global_load_dword v74, v[142:143], off nt
	v_lshl_add_u64 v[142:143], v[142:143], 0, s[26:27]
	global_load_dword v75, v[142:143], off nt
	v_lshl_add_u64 v[142:143], v[142:143], 0, s[26:27]
	global_load_dword v76, v[142:143], off nt
	v_lshl_add_u64 v[142:143], v[142:143], 0, s[26:27]
	global_load_dword v77, v[142:143], off nt
	v_lshl_add_u64 v[142:143], v[142:143], 0, s[26:27]
	global_load_dword v78, v[142:143], off nt
	v_lshl_add_u64 v[142:143], v[142:143], 0, s[26:27]
	global_load_dword v79, v[142:143], off nt
	v_lshl_add_u64 v[142:143], v[142:143], 0, s[26:27]
	global_load_dword v80, v[142:143], off nt
	v_lshl_add_u64 v[142:143], v[142:143], 0, s[26:27]
	global_load_dword v81, v[142:143], off nt
	v_lshl_add_u64 v[142:143], v[142:143], 0, s[26:27]
	global_load_dword v82, v[142:143], off nt
	v_lshl_add_u64 v[142:143], v[142:143], 0, s[26:27]
	global_load_dword v83, v[142:143], off nt
	v_lshl_add_u64 v[142:143], v[142:143], 0, s[26:27]
	global_load_dword v84, v[142:143], off nt
	v_lshl_add_u64 v[142:143], v[142:143], 0, s[26:27]
	global_load_dword v85, v[142:143], off nt
	v_lshl_add_u64 v[142:143], v[142:143], 0, s[26:27]
	global_load_dword v86, v[142:143], off nt
	v_lshl_add_u64 v[142:143], v[142:143], 0, s[26:27]
	global_load_dword v87, v[142:143], off nt
	s_branch .Lcvp_e1
.Lcvp_in1:
	s_sub_i32 s6, s4, 0xb00
	s_mul_i32 s7, s6, 0x38f
	s_lshr_b32 s7, s7, 16
	s_mul_i32 s8, s7, 0x48
	s_sub_i32 s6, s6, s8
	s_lshr_b32 s8, s6, 3
	s_lshl_b32 s8, s8, 8
	s_and_b32 s9, s6, 3
	s_lshl_b32 s9, s9, 6
	s_add_i32 s8, s8, s9
	s_bfe_u32 s9, s6, 0x10002
	s_lshl_b32 s9, s9, 5
	s_add_i32 s8, s8, s9
	s_lshl_b32 s8, s8, 2
	s_mul_i32 s9, s7, 0x90000
	s_add_u32 s10, s8, s9
	s_mov_b32 s11, 0
	v_lshl_add_u64 v[22:23], v[140:141], 0, s[10:11]
	s_mov_b64 s[26:27], 0x4800
	s_lshl_b32 s8, s6, 16
	s_lshl_b32 s9, s7, 7
	s_add_u32 s8, s8, s9
	s_add_u32 s8, s8, 0x1b00000
	s_add_u32 s12, s22, s8
	s_addc_u32 s13, s23, 0
	s_mov_b32 s1, 0
	global_load_dword v24, v[22:23], off nt
	v_lshl_add_u64 v[22:23], v[22:23], 0, s[26:27]
	global_load_dword v25, v[22:23], off nt
	v_lshl_add_u64 v[22:23], v[22:23], 0, s[26:27]
	global_load_dword v26, v[22:23], off nt
	v_lshl_add_u64 v[22:23], v[22:23], 0, s[26:27]
	global_load_dword v27, v[22:23], off nt
	v_lshl_add_u64 v[22:23], v[22:23], 0, s[26:27]
	global_load_dword v28, v[22:23], off nt
	v_lshl_add_u64 v[22:23], v[22:23], 0, s[26:27]
	global_load_dword v29, v[22:23], off nt
	v_lshl_add_u64 v[22:23], v[22:23], 0, s[26:27]
	global_load_dword v30, v[22:23], off nt
	v_lshl_add_u64 v[22:23], v[22:23], 0, s[26:27]
	global_load_dword v31, v[22:23], off nt
	v_lshl_add_u64 v[22:23], v[22:23], 0, s[26:27]
	global_load_dword v32, v[22:23], off nt
	v_lshl_add_u64 v[22:23], v[22:23], 0, s[26:27]
	global_load_dword v33, v[22:23], off nt
	v_lshl_add_u64 v[22:23], v[22:23], 0, s[26:27]
	global_load_dword v34, v[22:23], off nt
	v_lshl_add_u64 v[22:23], v[22:23], 0, s[26:27]
	global_load_dword v35, v[22:23], off nt
	v_lshl_add_u64 v[22:23], v[22:23], 0, s[26:27]
	global_load_dword v36, v[22:23], off nt
	v_lshl_add_u64 v[22:23], v[22:23], 0, s[26:27]
	global_load_dword v37, v[22:23], off nt
	v_lshl_add_u64 v[22:23], v[22:23], 0, s[26:27]
	global_load_dword v38, v[22:23], off nt
	v_lshl_add_u64 v[22:23], v[22:23], 0, s[26:27]
	global_load_dword v39, v[22:23], off nt
	v_lshl_add_u64 v[22:23], v[22:23], 0, s[26:27]
	global_load_dword v40, v[22:23], off nt
	v_lshl_add_u64 v[22:23], v[22:23], 0, s[26:27]
	global_load_dword v41, v[22:23], off nt
	v_lshl_add_u64 v[22:23], v[22:23], 0, s[26:27]
	global_load_dword v42, v[22:23], off nt
	v_lshl_add_u64 v[22:23], v[22:23], 0, s[26:27]
	global_load_dword v43, v[22:23], off nt
	v_lshl_add_u64 v[22:23], v[22:23], 0, s[26:27]
	global_load_dword v44, v[22:23], off nt
	v_lshl_add_u64 v[22:23], v[22:23], 0, s[26:27]
	global_load_dword v45, v[22:23], off nt
	v_lshl_add_u64 v[22:23], v[22:23], 0, s[26:27]
	global_load_dword v46, v[22:23], off nt
	v_lshl_add_u64 v[22:23], v[22:23], 0, s[26:27]
	global_load_dword v47, v[22:23], off nt
	v_lshl_add_u64 v[22:23], v[22:23], 0, s[26:27]
	global_load_dword v48, v[22:23], off nt
	v_lshl_add_u64 v[22:23], v[22:23], 0, s[26:27]
	global_load_dword v49, v[22:23], off nt
	v_lshl_add_u64 v[22:23], v[22:23], 0, s[26:27]
	global_load_dword v50, v[22:23], off nt
	v_lshl_add_u64 v[22:23], v[22:23], 0, s[26:27]
	global_load_dword v51, v[22:23], off nt
	v_lshl_add_u64 v[22:23], v[22:23], 0, s[26:27]
	global_load_dword v52, v[22:23], off nt
	v_lshl_add_u64 v[22:23], v[22:23], 0, s[26:27]
	global_load_dword v53, v[22:23], off nt
	v_lshl_add_u64 v[22:23], v[22:23], 0, s[26:27]
	global_load_dword v54, v[22:23], off nt
	v_lshl_add_u64 v[22:23], v[22:23], 0, s[26:27]
	global_load_dword v55, v[22:23], off nt

.Lcvp_wd:
	s_add_i32 s4, s4, s24
	s_cmp_lt_u32 s4, s25
	s_cbranch_scc0 .Lcvp_noload
	s_cmpk_lt_u32 s4, 0xb00
	s_cbranch_scc0 .Lcvp_in2
	s_cmpk_gt_u32 s4, 0x57f
	s_cselect_b32 s5, 1, 0
	s_mul_i32 s6, s5, 0x580
	s_sub_i32 s6, s4, s6
	s_mul_i32 s7, s6, 0x2e9
	s_lshr_b32 s7, s7, 16
	s_mul_i32 s8, s7, 0x58
	s_sub_i32 s6, s6, s8
	s_lshr_b32 s8, s6, 2
	s_and_b32 s9, s6, 3
	s_lshl_b32 s10, s8, 9
	s_lshl_b32 s11, s9, 7
	s_add_i32 s10, s10, s11
	s_mul_i32 s11, s5, 0xb00000
	s_add_u32 s10, s10, s11
	s_mul_i32 s11, s7, 0xb0000
	s_add_u32 s10, s10, s11
	s_mov_b32 s11, 0
	v_lshl_add_u64 v[22:23], v[136:137], 0, s[10:11]
	v_lshl_add_u64 v[142:143], v[138:139], 0, s[10:11]
	s_mov_b64 s[26:27], 0x5800
	s_lshl_b32 s8, s8, 3
	s_add_i32 s8, s8, s9
	s_mul_i32 s9, s5, 0xf80000
	s_lshl_b32 s8, s8, 16
	s_add_u32 s8, s8, s9
	s_lshl_b32 s9, s7, 7
	s_add_u32 s8, s8, s9
	s_add_u32 s8, s8, 0x1000000
	s_add_u32 s12, s22, s8
	s_addc_u32 s13, s23, 0
	s_mov_b32 s1, 1
	global_load_dword v24, v[22:23], off nt
	v_lshl_add_u64 v[22:23], v[22:23], 0, s[26:27]
	global_load_dword v25, v[22:23], off nt
	v_lshl_add_u64 v[22:23], v[22:23], 0, s[26:27]
	global_load_dword v26, v[22:23], off nt
	v_lshl_add_u64 v[22:23], v[22:23], 0, s[26:27]
	global_load_dword v27, v[22:23], off nt
	v_lshl_add_u64 v[22:23], v[22:23], 0, s[26:27]
	global_load_dword v28, v[22:23], off nt
	v_lshl_add_u64 v[22:23], v[22:23], 0, s[26:27]
	global_load_dword v29, v[22:23], off nt
	v_lshl_add_u64 v[22:23], v[22:23], 0, s[26:27]
	global_load_dword v30, v[22:23], off nt
	v_lshl_add_u64 v[22:23], v[22:23], 0, s[26:27]
	global_load_dword v31, v[22:23], off nt
	v_lshl_add_u64 v[22:23], v[22:23], 0, s[26:27]
	global_load_dword v32, v[22:23], off nt
	v_lshl_add_u64 v[22:23], v[22:23], 0, s[26:27]
	global_load_dword v33, v[22:23], off nt
	v_lshl_add_u64 v[22:23], v[22:23], 0, s[26:27]
	global_load_dword v34, v[22:23], off nt
	v_lshl_add_u64 v[22:23], v[22:23], 0, s[26:27]
	global_load_dword v35, v[22:23], off nt
	v_lshl_add_u64 v[22:23], v[22:23], 0, s[26:27]
	global_load_dword v36, v[22:23], off nt
	v_lshl_add_u64 v[22:23], v[22:23], 0, s[26:27]
	global_load_dword v37, v[22:23], off nt
	v_lshl_add_u64 v[22:23], v[22:23], 0, s[26:27]
	global_load_dword v38, v[22:23], off nt
	v_lshl_add_u64 v[22:23], v[22:23], 0, s[26:27]
	global_load_dword v39, v[22:23], off nt
	v_lshl_add_u64 v[22:23], v[22:23], 0, s[26:27]
	global_load_dword v40, v[22:23], off nt
	v_lshl_add_u64 v[22:23], v[22:23], 0, s[26:27]
	global_load_dword v41, v[22:23], off nt
	v_lshl_add_u64 v[22:23], v[22:23], 0, s[26:27]
	global_load_dword v42, v[22:23], off nt
	v_lshl_add_u64 v[22:23], v[22:23], 0, s[26:27]
	global_load_dword v43, v[22:23], off nt
	v_lshl_add_u64 v[22:23], v[22:23], 0, s[26:27]
	global_load_dword v44, v[22:23], off nt
	v_lshl_add_u64 v[22:23], v[22:23], 0, s[26:27]
	global_load_dword v45, v[22:23], off nt
	v_lshl_add_u64 v[22:23], v[22:23], 0, s[26:27]
	global_load_dword v46, v[22:23], off nt
	v_lshl_add_u64 v[22:23], v[22:23], 0, s[26:27]
	global_load_dword v47, v[22:23], off nt
	v_lshl_add_u64 v[22:23], v[22:23], 0, s[26:27]
	global_load_dword v48, v[22:23], off nt
	v_lshl_add_u64 v[22:23], v[22:23], 0, s[26:27]
	global_load_dword v49, v[22:23], off nt
	v_lshl_add_u64 v[22:23], v[22:23], 0, s[26:27]
	global_load_dword v50, v[22:23], off nt
	v_lshl_add_u64 v[22:23], v[22:23], 0, s[26:27]
	global_load_dword v51, v[22:23], off nt
	v_lshl_add_u64 v[22:23], v[22:23], 0, s[26:27]
	global_load_dword v52, v[22:23], off nt
	v_lshl_add_u64 v[22:23], v[22:23], 0, s[26:27]
	global_load_dword v53, v[22:23], off nt
	v_lshl_add_u64 v[22:23], v[22:23], 0, s[26:27]
	global_load_dword v54, v[22:23], off nt
	v_lshl_add_u64 v[22:23], v[22:23], 0, s[26:27]
	global_load_dword v55, v[22:23], off nt
	global_load_dword v56, v[142:143], off nt
	v_lshl_add_u64 v[142:143], v[142:143], 0, s[26:27]
	global_load_dword v57, v[142:143], off nt
	v_lshl_add_u64 v[142:143], v[142:143], 0, s[26:27]
	global_load_dword v58, v[142:143], off nt
	v_lshl_add_u64 v[142:143], v[142:143], 0, s[26:27]
	global_load_dword v59, v[142:143], off nt
	v_lshl_add_u64 v[142:143], v[142:143], 0, s[26:27]
	global_load_dword v60, v[142:143], off nt
	v_lshl_add_u64 v[142:143], v[142:143], 0, s[26:27]
	global_load_dword v61, v[142:143], off nt
	v_lshl_add_u64 v[142:143], v[142:143], 0, s[26:27]
	global_load_dword v62, v[142:143], off nt
	v_lshl_add_u64 v[142:143], v[142:143], 0, s[26:27]
	global_load_dword v63, v[142:143], off nt
	v_lshl_add_u64 v[142:143], v[142:143], 0, s[26:27]
	global_load_dword v64, v[142:143], off nt
	v_lshl_add_u64 v[142:143], v[142:143], 0, s[26:27]
	global_load_dword v65, v[142:143], off nt
	v_lshl_add_u64 v[142:143], v[142:143], 0, s[26:27]
	global_load_dword v66, v[142:143], off nt
	v_lshl_add_u64 v[142:143], v[142:143], 0, s[26:27]
	global_load_dword v67, v[142:143], off nt
	v_lshl_add_u64 v[142:143], v[142:143], 0, s[26:27]
	global_load_dword v68, v[142:143], off nt
	v_lshl_add_u64 v[142:143], v[142:143], 0, s[26:27]
	global_load_dword v69, v[142:143], off nt
	v_lshl_add_u64 v[142:143], v[142:143], 0, s[26:27]
	global_load_dword v70, v[142:143], off nt
	v_lshl_add_u64 v[142:143], v[142:143], 0, s[26:27]
	global_load_dword v71, v[142:143], off nt
	v_lshl_add_u64 v[142:143], v[142:143], 0, s[26:27]
	global_load_dword v72, v[142:143], off nt
	v_lshl_add_u64 v[142:143], v[142:143], 0, s[26:27]
	global_load_dword v73, v[142:143], off nt
	v_lshl_add_u64 v[142:143], v[142:143], 0, s[26:27]
	global_load_dword v74, v[142:143], off nt
	v_lshl_add_u64 v[142:143], v[142:143], 0, s[26:27]
	global_load_dword v75, v[142:143], off nt
	v_lshl_add_u64 v[142:143], v[142:143], 0, s[26:27]
	global_load_dword v76, v[142:143], off nt
	v_lshl_add_u64 v[142:143], v[142:143], 0, s[26:27]
	global_load_dword v77, v[142:143], off nt
	v_lshl_add_u64 v[142:143], v[142:143], 0, s[26:27]
	global_load_dword v78, v[142:143], off nt
	v_lshl_add_u64 v[142:143], v[142:143], 0, s[26:27]
	global_load_dword v79, v[142:143], off nt
	v_lshl_add_u64 v[142:143], v[142:143], 0, s[26:27]
	global_load_dword v80, v[142:143], off nt
	v_lshl_add_u64 v[142:143], v[142:143], 0, s[26:27]
	global_load_dword v81, v[142:143], off nt
	v_lshl_add_u64 v[142:143], v[142:143], 0, s[26:27]
	global_load_dword v82, v[142:143], off nt
	v_lshl_add_u64 v[142:143], v[142:143], 0, s[26:27]
	global_load_dword v83, v[142:143], off nt
	v_lshl_add_u64 v[142:143], v[142:143], 0, s[26:27]
	global_load_dword v84, v[142:143], off nt
	v_lshl_add_u64 v[142:143], v[142:143], 0, s[26:27]
	global_load_dword v85, v[142:143], off nt
	v_lshl_add_u64 v[142:143], v[142:143], 0, s[26:27]
	global_load_dword v86, v[142:143], off nt
	v_lshl_add_u64 v[142:143], v[142:143], 0, s[26:27]
	global_load_dword v87, v[142:143], off nt
	s_branch .Lcvp_e2

.Lcvp_done:
.LBB0_824:
	v_readlane_b32 s0, v252, 7
	v_readlane_b32 s1, v252, 8
	s_andn2_b64 vcc, exec, s[0:1]
	s_cbranch_vccnz .LBB0_855
	s_add_i32 s7, s10, 0x1a80
	s_cmpk_gt_i32 s7, 0x277f
	v_lshlrev_b32_e32 v5, 2, v8
	v_readlane_b32 s20, v252, 13
	s_cbranch_scc1 .LBB0_840
	v_and_or_b32 v4, v22, 4, v15
	v_readlane_b32 s36, v253, 33
	v_lshlrev_b32_e32 v0, 2, v4
	v_readlane_b32 s37, v253, 34
	v_readlane_b32 s38, v253, 35
	v_readlane_b32 s39, v253, 36
	v_readlane_b32 s40, v253, 37
	v_readlane_b32 s41, v253, 38
	v_readlane_b32 s42, v253, 39
	v_readlane_b32 s43, v253, 40
	v_readlane_b32 s0, v253, 41
	v_readlane_b32 s1, v253, 42
	v_lshl_add_u64 v[6:7], s[42:43], 0, v[0:1]
	v_readlane_b32 s36, v253, 25
	v_readlane_b32 s38, v253, 27
	v_readlane_b32 s39, v253, 28
	v_readlane_b32 s40, v253, 29
	v_readlane_b32 s41, v253, 30
	s_add_u32 s8, s0, 0x2a80000
	v_mul_u32_u24_e32 v12, 0x84, v2
	v_lshlrev_b32_e32 v0, 1, v2
	v_readlane_b32 s42, v253, 31
	v_readlane_b32 s43, v253, 32
	s_mov_b64 s[24:25], s[40:41]
	s_mov_b64 s[22:23], s[38:39]
	s_addc_u32 s9, s1, 0
	v_lshl_add_u64 v[10:11], s[0:1], 0, v[0:1]
	s_mov_b64 s[0:1], 0x3580000
	v_add3_u32 v24, s4, v12, v20
	v_mov_b32_e32 v0, s25
	v_mov_b32_e32 v12, s23
	v_cmp_eq_u32_e32 vcc, 0, v19
	v_lshl_add_u64 v[8:9], v[10:11], 0, s[0:1]
	s_mov_b64 s[0:1], 0x1b00000
	v_cndmask_b32_e32 v13, v0, v12, vcc
	v_mov_b32_e32 v0, s24
	v_mov_b32_e32 v12, s22
	v_add3_u32 v23, s4, v5, v21
	v_lshl_add_u64 v[10:11], v[10:11], 0, s[0:1]
	v_cndmask_b32_e32 v12, v0, v12, vcc
	s_lshl_b32 s11, s7, 5
	s_lshl_b32 s12, s20, 5
	s_lshl_b32 s13, s7, 1
	s_lshl_b32 s14, s20, 1
	v_readlane_b32 s37, v253, 26
	s_mov_b64 s[26:27], s[42:43]
	s_branch .LBB0_828
